# speedup vs baseline: 1.0079x; 1.0079x over previous
; __device__ __forceinline__ unsigned cvt_pk_bf16(float lo, float hi) { const f32x2 v = {lo, hi}; const bf16v2 r = __builtin_convertvector(v, bf16v2); return __builtin_bit_cast(unsigned, r); }
; __device__ __forceinline__ float silu_f(float g) { return g * __builtin_amdgcn_rcpf(1.0f + __expf(-g)); }
;     __device__ __forceinline__ void operator()(const f32x4 (&acc)[2][2][4][2], const Unit& u, int wr, int wc, int fr, int fq) const {
;         const int row0 = u.pm * BM + wr * 64 + fr, col0 = u.pn * HALF + wc * 32 + 8 * fq;
;         float rsv[2][4];
; #pragma unroll
;         for (int ai = 0; ai < 2; ++ai)
; #pragma unroll
;             for (int m = 0; m < 4; ++m) rsv[ai][m] = ss[wr * 64 + fr + ai * HALF + m * 16];
; #pragma unroll
;         for (int ai = 0; ai < 2; ++ai)
; #pragma unroll
;             for (int m = 0; m < 4; ++m) {
;                 const int row = row0 + ai * HALF + m * 16; const float rs = rsv[ai][m];
;                 bf16_t* rowp = O + (size_t)row * ldc + col0;
;                 const f32x4 g0 = acc[ai][0][m][0] * rs, g1 = acc[ai][0][m][1] * rs, u0 = acc[ai][1][m][0] * rs, u1 = acc[ai][1][m][1] * rs;
;                 u32x4 w;
;                 w.x = cvt_pk_bf16(silu_f(g0[0]) * u0[0], silu_f(g0[1]) * u0[1]); w.y = cvt_pk_bf16(silu_f(g0[2]) * u0[2], silu_f(g0[3]) * u0[3]);
;                 w.z = cvt_pk_bf16(silu_f(g1[0]) * u1[0], silu_f(g1[1]) * u1[1]); w.w = cvt_pk_bf16(silu_f(g1[2]) * u1[2], silu_f(g1[3]) * u1[3]);
;                 *(u32x4*)rowp = w;
;             }
.LBB0_651:
	v_add_u32_e32 v0, s48, v235
	s_lshl_b32 s0, s79, 2
	s_add_i32 s0, s91, s0
	v_lshl_add_u32 v130, v227, 2, s0
	s_waitcnt lgkmcnt(0)
	ds_read2_b32 v[138:139], v130 offset1:16
	ds_read2_b32 v[136:137], v130 offset0:32 offset1:48
	ds_read2_b32 v[134:135], v130 offset0:128 offset1:144
	ds_read2_b32 v[130:131], v130 offset0:160 offset1:176
	v_lshl_or_b32 v132, s63, 7, v232
	v_mov_b32_e32 v155, 0x2b00
	v_mul_lo_u32 v154, v0, v155
	v_lshl_add_u32 v154, v132, 1, v154
	v_mov_b32_e32 v156, 0xbfb8aa3b
	v_mov_b32_e32 v157, 0xbfb8aa3b
	v_mov_b32_e32 v158, 1.0
	v_mov_b32_e32 v159, 1.0
	s_waitcnt lgkmcnt(0)
	v_mov_b32_e32 v140, v138
	v_pk_mul_f32 v[126:127], v[126:127], v[140:141] op_sel_hi:[1,0]
	v_pk_mul_f32 v[128:129], v[128:129], v[140:141] op_sel_hi:[1,0]
	v_pk_mul_f32 v[122:123], v[122:123], v[140:141] op_sel_hi:[1,0]
	v_pk_mul_f32 v[124:125], v[124:125], v[140:141] op_sel_hi:[1,0]
	v_pk_mul_f32 v[94:95], v[94:95], v[140:141] op_sel_hi:[1,0]
	v_pk_mul_f32 v[96:97], v[96:97], v[140:141] op_sel_hi:[1,0]
	v_pk_mul_f32 v[90:91], v[90:91], v[140:141] op_sel_hi:[1,0]
	v_pk_mul_f32 v[92:93], v[92:93], v[140:141] op_sel_hi:[1,0]
	v_pk_mul_f32 v[142:143], v[126:127], v[156:157]
	v_pk_mul_f32 v[144:145], v[128:129], v[156:157]
	v_pk_mul_f32 v[146:147], v[122:123], v[156:157]
	v_pk_mul_f32 v[148:149], v[124:125], v[156:157]
	v_exp_f32_e32 v142, v142
	v_exp_f32_e32 v143, v143
	v_exp_f32_e32 v144, v144
	v_exp_f32_e32 v145, v145
	v_exp_f32_e32 v146, v146
	v_exp_f32_e32 v147, v147
	v_exp_f32_e32 v148, v148
	v_exp_f32_e32 v149, v149
	v_pk_add_f32 v[142:143], v[142:143], v[158:159]
	v_pk_add_f32 v[144:145], v[144:145], v[158:159]
	v_pk_add_f32 v[146:147], v[146:147], v[158:159]
	v_pk_add_f32 v[148:149], v[148:149], v[158:159]
	v_rcp_f32_e32 v142, v142
	v_rcp_f32_e32 v143, v143
	v_rcp_f32_e32 v144, v144
	v_rcp_f32_e32 v145, v145
	v_rcp_f32_e32 v146, v146
	v_rcp_f32_e32 v147, v147
	v_rcp_f32_e32 v148, v148
	v_rcp_f32_e32 v149, v149
	s_nop 0
	v_pk_mul_f32 v[126:127], v[126:127], v[142:143]
	v_pk_mul_f32 v[128:129], v[128:129], v[144:145]
	v_pk_mul_f32 v[122:123], v[122:123], v[146:147]
	v_pk_mul_f32 v[124:125], v[124:125], v[148:149]
	v_pk_mul_f32 v[126:127], v[94:95], v[126:127]
	v_pk_mul_f32 v[128:129], v[96:97], v[128:129]
	v_pk_mul_f32 v[122:123], v[90:91], v[122:123]
	v_pk_mul_f32 v[124:125], v[92:93], v[124:125]
	v_cvt_pk_bf16_f32 v150, v126, v127
	v_cvt_pk_bf16_f32 v151, v128, v129
	v_cvt_pk_bf16_f32 v152, v122, v123
	v_cvt_pk_bf16_f32 v153, v124, v125
	v_add_u32_e32 v155, 0x0, v154
	global_store_dwordx4 v155, v[150:153], s[6:7]
	v_mov_b32_e32 v140, v139
	v_pk_mul_f32 v[118:119], v[118:119], v[140:141] op_sel_hi:[1,0]
	v_pk_mul_f32 v[120:121], v[120:121], v[140:141] op_sel_hi:[1,0]
	v_pk_mul_f32 v[114:115], v[114:115], v[140:141] op_sel_hi:[1,0]
	v_pk_mul_f32 v[116:117], v[116:117], v[140:141] op_sel_hi:[1,0]
	v_pk_mul_f32 v[86:87], v[86:87], v[140:141] op_sel_hi:[1,0]
	v_pk_mul_f32 v[88:89], v[88:89], v[140:141] op_sel_hi:[1,0]
	v_pk_mul_f32 v[82:83], v[82:83], v[140:141] op_sel_hi:[1,0]
	v_pk_mul_f32 v[84:85], v[84:85], v[140:141] op_sel_hi:[1,0]
	v_pk_mul_f32 v[142:143], v[118:119], v[156:157]
	v_pk_mul_f32 v[144:145], v[120:121], v[156:157]
	v_pk_mul_f32 v[146:147], v[114:115], v[156:157]
	v_pk_mul_f32 v[148:149], v[116:117], v[156:157]
	v_exp_f32_e32 v142, v142
	v_exp_f32_e32 v143, v143
	v_exp_f32_e32 v144, v144
	v_exp_f32_e32 v145, v145
	v_exp_f32_e32 v146, v146
	v_exp_f32_e32 v147, v147
	v_exp_f32_e32 v148, v148
	v_exp_f32_e32 v149, v149
	v_pk_add_f32 v[142:143], v[142:143], v[158:159]
	v_pk_add_f32 v[144:145], v[144:145], v[158:159]
	v_pk_add_f32 v[146:147], v[146:147], v[158:159]
	v_pk_add_f32 v[148:149], v[148:149], v[158:159]
	v_rcp_f32_e32 v142, v142
	v_rcp_f32_e32 v143, v143
	v_rcp_f32_e32 v144, v144
	v_rcp_f32_e32 v145, v145
	v_rcp_f32_e32 v146, v146
	v_rcp_f32_e32 v147, v147
	v_rcp_f32_e32 v148, v148
	v_rcp_f32_e32 v149, v149
	s_nop 0
	v_pk_mul_f32 v[118:119], v[118:119], v[142:143]
	v_pk_mul_f32 v[120:121], v[120:121], v[144:145]
	v_pk_mul_f32 v[114:115], v[114:115], v[146:147]
	v_pk_mul_f32 v[116:117], v[116:117], v[148:149]
	v_pk_mul_f32 v[118:119], v[86:87], v[118:119]
	v_pk_mul_f32 v[120:121], v[88:89], v[120:121]
	v_pk_mul_f32 v[114:115], v[82:83], v[114:115]
	v_pk_mul_f32 v[116:117], v[84:85], v[116:117]
	v_cvt_pk_bf16_f32 v150, v118, v119
	v_cvt_pk_bf16_f32 v151, v120, v121
	v_cvt_pk_bf16_f32 v152, v114, v115
	v_cvt_pk_bf16_f32 v153, v116, v117
	v_add_u32_e32 v155, 0x2b000, v154
	global_store_dwordx4 v155, v[150:153], s[6:7]
	v_mov_b32_e32 v140, v136
	v_pk_mul_f32 v[110:111], v[110:111], v[140:141] op_sel_hi:[1,0]
	v_pk_mul_f32 v[112:113], v[112:113], v[140:141] op_sel_hi:[1,0]
	v_pk_mul_f32 v[106:107], v[106:107], v[140:141] op_sel_hi:[1,0]
	v_pk_mul_f32 v[108:109], v[108:109], v[140:141] op_sel_hi:[1,0]
	v_pk_mul_f32 v[78:79], v[78:79], v[140:141] op_sel_hi:[1,0]
	v_pk_mul_f32 v[80:81], v[80:81], v[140:141] op_sel_hi:[1,0]
	v_pk_mul_f32 v[74:75], v[74:75], v[140:141] op_sel_hi:[1,0]
	v_pk_mul_f32 v[76:77], v[76:77], v[140:141] op_sel_hi:[1,0]
	v_pk_mul_f32 v[142:143], v[110:111], v[156:157]
	v_pk_mul_f32 v[144:145], v[112:113], v[156:157]
	v_pk_mul_f32 v[146:147], v[106:107], v[156:157]
	v_pk_mul_f32 v[148:149], v[108:109], v[156:157]
	v_exp_f32_e32 v142, v142
	v_exp_f32_e32 v143, v143
	v_exp_f32_e32 v144, v144
	v_exp_f32_e32 v145, v145
	v_exp_f32_e32 v146, v146
	v_exp_f32_e32 v147, v147
	v_exp_f32_e32 v148, v148
	v_exp_f32_e32 v149, v149
	v_pk_add_f32 v[142:143], v[142:143], v[158:159]
	v_pk_add_f32 v[144:145], v[144:145], v[158:159]
	v_pk_add_f32 v[146:147], v[146:147], v[158:159]
	v_pk_add_f32 v[148:149], v[148:149], v[158:159]
; __device__ __forceinline__ unsigned cvt_pk_bf16(float lo, float hi) { const f32x2 v = {lo, hi}; const bf16v2 r = __builtin_convertvector(v, bf16v2); return __builtin_bit_cast(unsigned, r); }
; __device__ __forceinline__ float silu_f(float g) { return g * __builtin_amdgcn_rcpf(1.0f + __expf(-g)); }
;     __device__ __forceinline__ void operator()(const f32x4 (&acc)[2][2][4][2], const Unit& u, int wr, int wc, int fr, int fq) const {
;         const int row0 = u.pm * BM + wr * 64 + fr, col0 = u.pn * HALF + wc * 32 + 8 * fq;
;         float rsv[2][4];
; #pragma unroll
;         for (int ai = 0; ai < 2; ++ai)
; #pragma unroll
;             for (int m = 0; m < 4; ++m) rsv[ai][m] = ss[wr * 64 + fr + ai * HALF + m * 16];
; #pragma unroll
;         for (int ai = 0; ai < 2; ++ai)
; #pragma unroll
;             for (int m = 0; m < 4; ++m) {
;                 const int row = row0 + ai * HALF + m * 16; const float rs = rsv[ai][m];
;                 bf16_t* rowp = O + (size_t)row * ldc + col0;
;                 const f32x4 g0 = acc[ai][0][m][0] * rs, g1 = acc[ai][0][m][1] * rs, u0 = acc[ai][1][m][0] * rs, u1 = acc[ai][1][m][1] * rs;
;                 u32x4 w;
;                 w.x = cvt_pk_bf16(silu_f(g0[0]) * u0[0], silu_f(g0[1]) * u0[1]); w.y = cvt_pk_bf16(silu_f(g0[2]) * u0[2], silu_f(g0[3]) * u0[3]);
;                 w.z = cvt_pk_bf16(silu_f(g1[0]) * u1[0], silu_f(g1[1]) * u1[1]); w.w = cvt_pk_bf16(silu_f(g1[2]) * u1[2], silu_f(g1[3]) * u1[3]);
;                 *(u32x4*)rowp = w;
;             }
	v_rcp_f32_e32 v142, v142
	v_rcp_f32_e32 v143, v143
	v_rcp_f32_e32 v144, v144
	v_rcp_f32_e32 v145, v145
	v_rcp_f32_e32 v146, v146
	v_rcp_f32_e32 v147, v147
	v_rcp_f32_e32 v148, v148
	v_rcp_f32_e32 v149, v149
	s_nop 0
	v_pk_mul_f32 v[110:111], v[110:111], v[142:143]
	v_pk_mul_f32 v[112:113], v[112:113], v[144:145]
	v_pk_mul_f32 v[106:107], v[106:107], v[146:147]
	v_pk_mul_f32 v[108:109], v[108:109], v[148:149]
	v_pk_mul_f32 v[110:111], v[78:79], v[110:111]
	v_pk_mul_f32 v[112:113], v[80:81], v[112:113]
	v_pk_mul_f32 v[106:107], v[74:75], v[106:107]
	v_pk_mul_f32 v[108:109], v[76:77], v[108:109]
	v_cvt_pk_bf16_f32 v150, v110, v111
	v_cvt_pk_bf16_f32 v151, v112, v113
	v_cvt_pk_bf16_f32 v152, v106, v107
	v_cvt_pk_bf16_f32 v153, v108, v109
	v_add_u32_e32 v155, 0x56000, v154
	global_store_dwordx4 v155, v[150:153], s[6:7]
	v_mov_b32_e32 v140, v137
	v_pk_mul_f32 v[102:103], v[102:103], v[140:141] op_sel_hi:[1,0]
	v_pk_mul_f32 v[104:105], v[104:105], v[140:141] op_sel_hi:[1,0]
	v_pk_mul_f32 v[98:99], v[98:99], v[140:141] op_sel_hi:[1,0]
	v_pk_mul_f32 v[100:101], v[100:101], v[140:141] op_sel_hi:[1,0]
	v_pk_mul_f32 v[70:71], v[70:71], v[140:141] op_sel_hi:[1,0]
	v_pk_mul_f32 v[72:73], v[72:73], v[140:141] op_sel_hi:[1,0]
	v_pk_mul_f32 v[66:67], v[66:67], v[140:141] op_sel_hi:[1,0]
	v_pk_mul_f32 v[68:69], v[68:69], v[140:141] op_sel_hi:[1,0]
	v_pk_mul_f32 v[142:143], v[102:103], v[156:157]
	v_pk_mul_f32 v[144:145], v[104:105], v[156:157]
	v_pk_mul_f32 v[146:147], v[98:99], v[156:157]
	v_pk_mul_f32 v[148:149], v[100:101], v[156:157]
	v_exp_f32_e32 v142, v142
	v_exp_f32_e32 v143, v143
	v_exp_f32_e32 v144, v144
	v_exp_f32_e32 v145, v145
	v_exp_f32_e32 v146, v146
	v_exp_f32_e32 v147, v147
	v_exp_f32_e32 v148, v148
	v_exp_f32_e32 v149, v149
	v_pk_add_f32 v[142:143], v[142:143], v[158:159]
	v_pk_add_f32 v[144:145], v[144:145], v[158:159]
	v_pk_add_f32 v[146:147], v[146:147], v[158:159]
	v_pk_add_f32 v[148:149], v[148:149], v[158:159]
	v_rcp_f32_e32 v142, v142
	v_rcp_f32_e32 v143, v143
	v_rcp_f32_e32 v144, v144
	v_rcp_f32_e32 v145, v145
	v_rcp_f32_e32 v146, v146
	v_rcp_f32_e32 v147, v147
	v_rcp_f32_e32 v148, v148
	v_rcp_f32_e32 v149, v149
	s_nop 0
	v_pk_mul_f32 v[102:103], v[102:103], v[142:143]
	v_pk_mul_f32 v[104:105], v[104:105], v[144:145]
	v_pk_mul_f32 v[98:99], v[98:99], v[146:147]
	v_pk_mul_f32 v[100:101], v[100:101], v[148:149]
	v_pk_mul_f32 v[102:103], v[70:71], v[102:103]
	v_pk_mul_f32 v[104:105], v[72:73], v[104:105]
	v_pk_mul_f32 v[98:99], v[66:67], v[98:99]
	v_pk_mul_f32 v[100:101], v[68:69], v[100:101]
	v_cvt_pk_bf16_f32 v150, v102, v103
	v_cvt_pk_bf16_f32 v151, v104, v105
	v_cvt_pk_bf16_f32 v152, v98, v99
	v_cvt_pk_bf16_f32 v153, v100, v101
	v_add_u32_e32 v155, 0x81000, v154
	global_store_dwordx4 v155, v[150:153], s[6:7]
	v_mov_b32_e32 v140, v134
	v_pk_mul_f32 v[62:63], v[62:63], v[140:141] op_sel_hi:[1,0]
	v_pk_mul_f32 v[64:65], v[64:65], v[140:141] op_sel_hi:[1,0]
	v_pk_mul_f32 v[58:59], v[58:59], v[140:141] op_sel_hi:[1,0]
	v_pk_mul_f32 v[60:61], v[60:61], v[140:141] op_sel_hi:[1,0]
	v_pk_mul_f32 v[30:31], v[30:31], v[140:141] op_sel_hi:[1,0]
	v_pk_mul_f32 v[32:33], v[32:33], v[140:141] op_sel_hi:[1,0]
	v_pk_mul_f32 v[26:27], v[26:27], v[140:141] op_sel_hi:[1,0]
	v_pk_mul_f32 v[28:29], v[28:29], v[140:141] op_sel_hi:[1,0]
	v_pk_mul_f32 v[142:143], v[62:63], v[156:157]
	v_pk_mul_f32 v[144:145], v[64:65], v[156:157]
	v_pk_mul_f32 v[146:147], v[58:59], v[156:157]
	v_pk_mul_f32 v[148:149], v[60:61], v[156:157]
	v_exp_f32_e32 v142, v142
	v_exp_f32_e32 v143, v143
	v_exp_f32_e32 v144, v144
	v_exp_f32_e32 v145, v145
	v_exp_f32_e32 v146, v146
	v_exp_f32_e32 v147, v147
	v_exp_f32_e32 v148, v148
	v_exp_f32_e32 v149, v149
	v_pk_add_f32 v[142:143], v[142:143], v[158:159]
	v_pk_add_f32 v[144:145], v[144:145], v[158:159]
	v_pk_add_f32 v[146:147], v[146:147], v[158:159]
	v_pk_add_f32 v[148:149], v[148:149], v[158:159]
	v_rcp_f32_e32 v142, v142
	v_rcp_f32_e32 v143, v143
	v_rcp_f32_e32 v144, v144
	v_rcp_f32_e32 v145, v145
	v_rcp_f32_e32 v146, v146
	v_rcp_f32_e32 v147, v147
	v_rcp_f32_e32 v148, v148
	v_rcp_f32_e32 v149, v149
	s_nop 0
	v_pk_mul_f32 v[62:63], v[62:63], v[142:143]
	v_pk_mul_f32 v[64:65], v[64:65], v[144:145]
	v_pk_mul_f32 v[58:59], v[58:59], v[146:147]
	v_pk_mul_f32 v[60:61], v[60:61], v[148:149]
	v_pk_mul_f32 v[62:63], v[30:31], v[62:63]
	v_pk_mul_f32 v[64:65], v[32:33], v[64:65]
	v_pk_mul_f32 v[58:59], v[26:27], v[58:59]
	v_pk_mul_f32 v[60:61], v[28:29], v[60:61]
	v_cvt_pk_bf16_f32 v150, v62, v63
	v_cvt_pk_bf16_f32 v151, v64, v65
	v_cvt_pk_bf16_f32 v152, v58, v59
	v_cvt_pk_bf16_f32 v153, v60, v61
	v_add_u32_e32 v155, 0x158000, v154
	global_store_dwordx4 v155, v[150:153], s[6:7]
	v_mov_b32_e32 v140, v135
	v_pk_mul_f32 v[54:55], v[54:55], v[140:141] op_sel_hi:[1,0]
	v_pk_mul_f32 v[56:57], v[56:57], v[140:141] op_sel_hi:[1,0]
	v_pk_mul_f32 v[50:51], v[50:51], v[140:141] op_sel_hi:[1,0]
	v_pk_mul_f32 v[52:53], v[52:53], v[140:141] op_sel_hi:[1,0]
	v_pk_mul_f32 v[22:23], v[22:23], v[140:141] op_sel_hi:[1,0]
	v_pk_mul_f32 v[24:25], v[24:25], v[140:141] op_sel_hi:[1,0]
	v_pk_mul_f32 v[18:19], v[18:19], v[140:141] op_sel_hi:[1,0]
	v_pk_mul_f32 v[20:21], v[20:21], v[140:141] op_sel_hi:[1,0]
; __device__ __forceinline__ unsigned cvt_pk_bf16(float lo, float hi) { const f32x2 v = {lo, hi}; const bf16v2 r = __builtin_convertvector(v, bf16v2); return __builtin_bit_cast(unsigned, r); }
; __device__ __forceinline__ float silu_f(float g) { return g * __builtin_amdgcn_rcpf(1.0f + __expf(-g)); }
;     __device__ __forceinline__ void operator()(const f32x4 (&acc)[2][2][4][2], const Unit& u, int wr, int wc, int fr, int fq) const {
;         const int row0 = u.pm * BM + wr * 64 + fr, col0 = u.pn * HALF + wc * 32 + 8 * fq;
;         float rsv[2][4];
; #pragma unroll
;         for (int ai = 0; ai < 2; ++ai)
; #pragma unroll
;             for (int m = 0; m < 4; ++m) rsv[ai][m] = ss[wr * 64 + fr + ai * HALF + m * 16];
; #pragma unroll
;         for (int ai = 0; ai < 2; ++ai)
; #pragma unroll
;             for (int m = 0; m < 4; ++m) {
;                 const int row = row0 + ai * HALF + m * 16; const float rs = rsv[ai][m];
;                 bf16_t* rowp = O + (size_t)row * ldc + col0;
;                 const f32x4 g0 = acc[ai][0][m][0] * rs, g1 = acc[ai][0][m][1] * rs, u0 = acc[ai][1][m][0] * rs, u1 = acc[ai][1][m][1] * rs;
;                 u32x4 w;
;                 w.x = cvt_pk_bf16(silu_f(g0[0]) * u0[0], silu_f(g0[1]) * u0[1]); w.y = cvt_pk_bf16(silu_f(g0[2]) * u0[2], silu_f(g0[3]) * u0[3]);
;                 w.z = cvt_pk_bf16(silu_f(g1[0]) * u1[0], silu_f(g1[1]) * u1[1]); w.w = cvt_pk_bf16(silu_f(g1[2]) * u1[2], silu_f(g1[3]) * u1[3]);
;                 *(u32x4*)rowp = w;
;             }
	v_pk_mul_f32 v[142:143], v[54:55], v[156:157]
	v_pk_mul_f32 v[144:145], v[56:57], v[156:157]
	v_pk_mul_f32 v[146:147], v[50:51], v[156:157]
	v_pk_mul_f32 v[148:149], v[52:53], v[156:157]
	v_exp_f32_e32 v142, v142
	v_exp_f32_e32 v143, v143
	v_exp_f32_e32 v144, v144
	v_exp_f32_e32 v145, v145
	v_exp_f32_e32 v146, v146
	v_exp_f32_e32 v147, v147
	v_exp_f32_e32 v148, v148
	v_exp_f32_e32 v149, v149
	v_pk_add_f32 v[142:143], v[142:143], v[158:159]
	v_pk_add_f32 v[144:145], v[144:145], v[158:159]
	v_pk_add_f32 v[146:147], v[146:147], v[158:159]
	v_pk_add_f32 v[148:149], v[148:149], v[158:159]
	v_rcp_f32_e32 v142, v142
	v_rcp_f32_e32 v143, v143
	v_rcp_f32_e32 v144, v144
	v_rcp_f32_e32 v145, v145
	v_rcp_f32_e32 v146, v146
	v_rcp_f32_e32 v147, v147
	v_rcp_f32_e32 v148, v148
	v_rcp_f32_e32 v149, v149
	s_nop 0
	v_pk_mul_f32 v[54:55], v[54:55], v[142:143]
	v_pk_mul_f32 v[56:57], v[56:57], v[144:145]
	v_pk_mul_f32 v[50:51], v[50:51], v[146:147]
	v_pk_mul_f32 v[52:53], v[52:53], v[148:149]
	v_pk_mul_f32 v[54:55], v[22:23], v[54:55]
	v_pk_mul_f32 v[56:57], v[24:25], v[56:57]
	v_pk_mul_f32 v[50:51], v[18:19], v[50:51]
	v_pk_mul_f32 v[52:53], v[20:21], v[52:53]
	v_cvt_pk_bf16_f32 v150, v54, v55
	v_cvt_pk_bf16_f32 v151, v56, v57
	v_cvt_pk_bf16_f32 v152, v50, v51
	v_cvt_pk_bf16_f32 v153, v52, v53
	v_add_u32_e32 v155, 0x183000, v154
	global_store_dwordx4 v155, v[150:153], s[6:7]
	v_mov_b32_e32 v140, v130
	v_pk_mul_f32 v[46:47], v[46:47], v[140:141] op_sel_hi:[1,0]
	v_pk_mul_f32 v[48:49], v[48:49], v[140:141] op_sel_hi:[1,0]
	v_pk_mul_f32 v[42:43], v[42:43], v[140:141] op_sel_hi:[1,0]
	v_pk_mul_f32 v[44:45], v[44:45], v[140:141] op_sel_hi:[1,0]
	v_pk_mul_f32 v[14:15], v[14:15], v[140:141] op_sel_hi:[1,0]
	v_pk_mul_f32 v[16:17], v[16:17], v[140:141] op_sel_hi:[1,0]
	v_pk_mul_f32 v[10:11], v[10:11], v[140:141] op_sel_hi:[1,0]
	v_pk_mul_f32 v[12:13], v[12:13], v[140:141] op_sel_hi:[1,0]
	v_pk_mul_f32 v[142:143], v[46:47], v[156:157]
	v_pk_mul_f32 v[144:145], v[48:49], v[156:157]
	v_pk_mul_f32 v[146:147], v[42:43], v[156:157]
	v_pk_mul_f32 v[148:149], v[44:45], v[156:157]
	v_exp_f32_e32 v142, v142
	v_exp_f32_e32 v143, v143
	v_exp_f32_e32 v144, v144
	v_exp_f32_e32 v145, v145
	v_exp_f32_e32 v146, v146
	v_exp_f32_e32 v147, v147
	v_exp_f32_e32 v148, v148
	v_exp_f32_e32 v149, v149
	v_pk_add_f32 v[142:143], v[142:143], v[158:159]
	v_pk_add_f32 v[144:145], v[144:145], v[158:159]
	v_pk_add_f32 v[146:147], v[146:147], v[158:159]
	v_pk_add_f32 v[148:149], v[148:149], v[158:159]
	v_rcp_f32_e32 v142, v142
	v_rcp_f32_e32 v143, v143
	v_rcp_f32_e32 v144, v144
	v_rcp_f32_e32 v145, v145
	v_rcp_f32_e32 v146, v146
	v_rcp_f32_e32 v147, v147
	v_rcp_f32_e32 v148, v148
	v_rcp_f32_e32 v149, v149
	s_nop 0
	v_pk_mul_f32 v[46:47], v[46:47], v[142:143]
	v_pk_mul_f32 v[48:49], v[48:49], v[144:145]
	v_pk_mul_f32 v[42:43], v[42:43], v[146:147]
	v_pk_mul_f32 v[44:45], v[44:45], v[148:149]
	v_pk_mul_f32 v[46:47], v[14:15], v[46:47]
	v_pk_mul_f32 v[48:49], v[16:17], v[48:49]
	v_pk_mul_f32 v[42:43], v[10:11], v[42:43]
	v_pk_mul_f32 v[44:45], v[12:13], v[44:45]
	v_cvt_pk_bf16_f32 v150, v46, v47
	v_cvt_pk_bf16_f32 v151, v48, v49
	v_cvt_pk_bf16_f32 v152, v42, v43
	v_cvt_pk_bf16_f32 v153, v44, v45
	v_add_u32_e32 v155, 0x1ae000, v154
	global_store_dwordx4 v155, v[150:153], s[6:7]
	v_mov_b32_e32 v140, v131
	v_pk_mul_f32 v[38:39], v[38:39], v[140:141] op_sel_hi:[1,0]
	v_pk_mul_f32 v[40:41], v[40:41], v[140:141] op_sel_hi:[1,0]
	v_pk_mul_f32 v[34:35], v[34:35], v[140:141] op_sel_hi:[1,0]
	v_pk_mul_f32 v[36:37], v[36:37], v[140:141] op_sel_hi:[1,0]
	v_pk_mul_f32 v[6:7], v[6:7], v[140:141] op_sel_hi:[1,0]
	v_pk_mul_f32 v[8:9], v[8:9], v[140:141] op_sel_hi:[1,0]
	v_pk_mul_f32 v[2:3], v[2:3], v[140:141] op_sel_hi:[1,0]
	v_pk_mul_f32 v[4:5], v[4:5], v[140:141] op_sel_hi:[1,0]
	v_pk_mul_f32 v[142:143], v[38:39], v[156:157]
	v_pk_mul_f32 v[144:145], v[40:41], v[156:157]
	v_pk_mul_f32 v[146:147], v[34:35], v[156:157]
	v_pk_mul_f32 v[148:149], v[36:37], v[156:157]
	v_exp_f32_e32 v142, v142
	v_exp_f32_e32 v143, v143
	v_exp_f32_e32 v144, v144
	v_exp_f32_e32 v145, v145
	v_exp_f32_e32 v146, v146
	v_exp_f32_e32 v147, v147
	v_exp_f32_e32 v148, v148
	v_exp_f32_e32 v149, v149
	v_pk_add_f32 v[142:143], v[142:143], v[158:159]
	v_pk_add_f32 v[144:145], v[144:145], v[158:159]
	v_pk_add_f32 v[146:147], v[146:147], v[158:159]
	v_pk_add_f32 v[148:149], v[148:149], v[158:159]
	v_rcp_f32_e32 v142, v142
	v_rcp_f32_e32 v143, v143
	v_rcp_f32_e32 v144, v144
	v_rcp_f32_e32 v145, v145
	v_rcp_f32_e32 v146, v146
	v_rcp_f32_e32 v147, v147
	v_rcp_f32_e32 v148, v148
	v_rcp_f32_e32 v149, v149
	s_nop 0
	v_pk_mul_f32 v[38:39], v[38:39], v[142:143]
	v_pk_mul_f32 v[40:41], v[40:41], v[144:145]
	v_pk_mul_f32 v[34:35], v[34:35], v[146:147]
	v_pk_mul_f32 v[36:37], v[36:37], v[148:149]
	v_pk_mul_f32 v[38:39], v[6:7], v[38:39]
	v_pk_mul_f32 v[40:41], v[8:9], v[40:41]
	v_pk_mul_f32 v[34:35], v[2:3], v[34:35]
	v_pk_mul_f32 v[36:37], v[4:5], v[36:37]
	v_cvt_pk_bf16_f32 v150, v38, v39
	v_cvt_pk_bf16_f32 v151, v40, v41
	v_cvt_pk_bf16_f32 v152, v34, v35
	v_cvt_pk_bf16_f32 v153, v36, v37
	v_add_u32_e32 v155, 0x1d9000, v154
	global_store_dwordx4 v155, v[150:153], s[6:7]
	s_and_b64 vcc, exec, s[42:43]
	s_cbranch_vccnz .LBB0_491
